# only change vs baseline: ew_init prologue loop processes 4 rows per iteration with 16 loads in flight
# speedup vs baseline: 1.0058x; 1.0058x over previous
; #define PL_UNPACK(dst0, dst1, w_) do { dst0 = (f32x4){bf_lo((w_).x), bf_hi((w_).x), bf_lo((w_).y), bf_hi((w_).y)}; dst1 = (f32x4){bf_lo((w_).z), bf_hi((w_).z), bf_lo((w_).w), bf_hi((w_).w)}; } while (0)
; __device__ __forceinline__ void pool_unit(const float* P, const bf16* WPT, bf16* OPOOL, int pu, int lane) {
;     ...
;     for (int j = 1; j < w; ++j) {
;         const bool ok = j <= tl; const float wg = ok ? 1.f : 0.f; const bf16* q = pp - (size_t)(ok ? j : 0) * 256;
; #pragma unroll
;         for (int kk = 0; kk < 4; ++kk) { const v4u w_ = *(const v4u*)(q + kk * 16); f32x4 a_, b_; PL_UNPACK(a_, b_, w_); s[kk][0] += wg * a_; s[kk][1] += wg * b_; }
;     }
;     ...
;     const float inv = 1.0f / (float)(tl + 1 < w ? tl + 1 : w);
;     f32x16 acc0, acc1;
; #pragma unroll
;     for (int i = 0; i < 16; ++i) { acc0[i] = 0.f; acc1[i] = 0.f; }
;     const bf16* wp = WPT + (size_t)(g * 64 + r) * 64 + 8 * hh;
; #pragma unroll
;     for (int kk = 0; kk < 4; ++kk) {
;         float a[8];
; #pragma unroll
;         for (int e = 0; e < 4; ++e) { a[e] = s[kk][0][e] * inv - p0[kk][0][e]; a[4 + e] = s[kk][1][e] * inv - p0[kk][1][e]; }
;         const bf16x8 pf = pack8(a);
.LBB0_113:
	v_mov_b32_e32 v23, s41
	v_cmp_gt_u32_e32 vcc, s41, v22
	s_add_i32 s41, s41, 1
	s_cmp_lg_u32 s40, s41
	v_cndmask_b32_e64 v23, v23, 0, vcc
	v_mad_u64_u32 v[106:107], s[42:43], v23, s0, v[8:9]
	v_sub_u32_e32 v107, v107, v23
	global_load_dwordx4 v[24:27], v[106:107], off
	global_load_dwordx4 v[28:31], v[106:107], off offset:32
	global_load_dwordx4 v[102:105], v[106:107], off offset:64
	s_nop 0
	global_load_dwordx4 v[106:109], v[106:107], off offset:96
	v_cndmask_b32_e64 v110, 1.0, 0, vcc
	s_waitcnt vmcnt(0)
	v_lshlrev_b32_e32 v112, 16, v24
	v_and_b32_e32 v113, 0xffff0000, v24
	v_lshlrev_b32_e32 v24, 16, v25
	v_and_b32_e32 v25, 0xffff0000, v25
	v_lshlrev_b32_e32 v114, 16, v26
	v_and_b32_e32 v115, 0xffff0000, v26
	v_lshlrev_b32_e32 v26, 16, v27
	v_and_b32_e32 v27, 0xffff0000, v27
	s_waitcnt vmcnt(2)
	v_lshlrev_b32_e32 v116, 16, v28
	v_and_b32_e32 v117, 0xffff0000, v28
	v_lshlrev_b32_e32 v28, 16, v29
	v_and_b32_e32 v29, 0xffff0000, v29
	v_lshlrev_b32_e32 v118, 16, v30
	v_and_b32_e32 v119, 0xffff0000, v30
	v_lshlrev_b32_e32 v30, 16, v31
	v_and_b32_e32 v31, 0xffff0000, v31
	s_waitcnt vmcnt(1)
	v_lshlrev_b32_e32 v120, 16, v102
	v_and_b32_e32 v121, 0xffff0000, v102
	v_lshlrev_b32_e32 v102, 16, v103
	v_and_b32_e32 v103, 0xffff0000, v103
	v_lshlrev_b32_e32 v122, 16, v104
	v_and_b32_e32 v123, 0xffff0000, v104
	v_lshlrev_b32_e32 v104, 16, v105
	v_and_b32_e32 v105, 0xffff0000, v105
	s_waitcnt vmcnt(0)
	v_lshlrev_b32_e32 v124, 16, v106
	v_and_b32_e32 v125, 0xffff0000, v106
	v_lshlrev_b32_e32 v106, 16, v107
	v_and_b32_e32 v107, 0xffff0000, v107
	v_lshlrev_b32_e32 v126, 16, v108
	v_and_b32_e32 v127, 0xffff0000, v108
	v_lshlrev_b32_e32 v108, 16, v109
	v_and_b32_e32 v109, 0xffff0000, v109
	v_pk_fma_f32 v[10:11], v[110:111], v[24:25], v[10:11] op_sel_hi:[0,1,1]
	v_pk_fma_f32 v[12:13], v[110:111], v[112:113], v[12:13] op_sel_hi:[0,1,1]
	v_pk_fma_f32 v[14:15], v[110:111], v[26:27], v[14:15] op_sel_hi:[0,1,1]
	v_pk_fma_f32 v[20:21], v[110:111], v[114:115], v[20:21] op_sel_hi:[0,1,1]
	v_pk_fma_f32 v[96:97], v[110:111], v[28:29], v[96:97] op_sel_hi:[0,1,1]
	v_pk_fma_f32 v[18:19], v[110:111], v[116:117], v[18:19] op_sel_hi:[0,1,1]
	v_pk_fma_f32 v[98:99], v[110:111], v[30:31], v[98:99] op_sel_hi:[0,1,1]
	v_pk_fma_f32 v[100:101], v[110:111], v[118:119], v[100:101] op_sel_hi:[0,1,1]
	v_pk_fma_f32 v[58:59], v[110:111], v[102:103], v[58:59] op_sel_hi:[0,1,1]
	v_pk_fma_f32 v[60:61], v[110:111], v[120:121], v[60:61] op_sel_hi:[0,1,1]
	v_pk_fma_f32 v[62:63], v[110:111], v[104:105], v[62:63] op_sel_hi:[0,1,1]
	v_pk_fma_f32 v[64:65], v[110:111], v[122:123], v[64:65] op_sel_hi:[0,1,1]
	v_pk_fma_f32 v[50:51], v[110:111], v[106:107], v[50:51] op_sel_hi:[0,1,1]
	v_pk_fma_f32 v[52:53], v[110:111], v[124:125], v[52:53] op_sel_hi:[0,1,1]
	v_pk_fma_f32 v[54:55], v[110:111], v[108:109], v[54:55] op_sel_hi:[0,1,1]
	v_pk_fma_f32 v[56:57], v[110:111], v[126:127], v[56:57] op_sel_hi:[0,1,1]
	s_cbranch_scc1 .LBB0_113
	global_load_dwordx4 v[24:27], v[82:83], off
	global_load_dwordx4 v[28:31], v[84:85], off
	global_load_dwordx4 v[102:105], v[82:83], off offset:32
	v_add_u32_e32 v8, 1, v22
	v_min_u32_e32 v8, s40, v8
	v_cvt_f32_ubyte0_e32 v8, v8
	v_div_scale_f32 v9, s[42:43], v8, v8, 1.0
	v_rcp_f32_e32 v22, v9
	v_div_scale_f32 v23, vcc, 1.0, v8, 1.0
	global_load_dwordx4 v[106:109], v[88:89], off
	global_load_dwordx4 v[110:113], v[82:83], off offset:64
	v_fma_f32 v33, -v9, v22, 1.0
	v_fmac_f32_e32 v22, v33, v22
	v_mul_f32_e32 v33, v23, v22
	v_fma_f32 v73, -v9, v33, v23
	v_fmac_f32_e32 v33, v73, v22
	v_fma_f32 v9, -v9, v33, v23
	v_div_fmas_f32 v9, v9, v22, v33
	v_div_fixup_f32 v114, v9, v8, 1.0
	v_pk_fma_f32 v[2:3], v[114:115], v[12:13], v[2:3] op_sel_hi:[0,1,1] neg_lo:[0,0,1] neg_hi:[0,0,1]
	v_pk_fma_f32 v[6:7], v[114:115], v[20:21], v[6:7] op_sel_hi:[0,1,1] neg_lo:[0,0,1] neg_hi:[0,0,1]
	v_pk_fma_f32 v[0:1], v[114:115], v[10:11], v[0:1] op_sel_hi:[0,1,1] neg_lo:[0,0,1] neg_hi:[0,0,1]
	v_pk_fma_f32 v[4:5], v[114:115], v[14:15], v[4:5] op_sel_hi:[0,1,1] neg_lo:[0,0,1] neg_hi:[0,0,1]
	v_cvt_pk_bf16_f32 v20, v2, v3
	v_cvt_pk_bf16_f32 v21, v0, v1
	v_cvt_pk_bf16_f32 v22, v6, v7
	v_cvt_pk_bf16_f32 v23, v4, v5
	v_pk_fma_f32 v[116:117], v[114:115], v[18:19], v[16:17] op_sel_hi:[0,1,1] neg_lo:[0,0,1] neg_hi:[0,0,1]
	v_pk_fma_f32 v[70:71], v[114:115], v[100:101], v[70:71] op_sel_hi:[0,1,1] neg_lo:[0,0,1] neg_hi:[0,0,1]
	v_pk_fma_f32 v[96:97], v[114:115], v[96:97], v[66:67] op_sel_hi:[0,1,1] neg_lo:[0,0,1] neg_hi:[0,0,1]
	v_pk_fma_f32 v[98:99], v[114:115], v[98:99], v[68:69] op_sel_hi:[0,1,1] neg_lo:[0,0,1] neg_hi:[0,0,1]
	v_cvt_pk_bf16_f32 v66, v116, v117
	v_cvt_pk_bf16_f32 v67, v96, v97
	v_cvt_pk_bf16_f32 v68, v70, v71
	v_cvt_pk_bf16_f32 v69, v98, v99
	v_pk_fma_f32 v[44:45], v[114:115], v[60:61], v[44:45] op_sel_hi:[0,1,1] neg_lo:[0,0,1] neg_hi:[0,0,1]
	v_pk_fma_f32 v[48:49], v[114:115], v[64:65], v[48:49] op_sel_hi:[0,1,1] neg_lo:[0,0,1] neg_hi:[0,0,1]
	v_pk_fma_f32 v[46:47], v[114:115], v[62:63], v[46:47] op_sel_hi:[0,1,1] neg_lo:[0,0,1] neg_hi:[0,0,1]
	v_pk_fma_f32 v[58:59], v[114:115], v[58:59], v[42:43] op_sel_hi:[0,1,1] neg_lo:[0,0,1] neg_hi:[0,0,1]
	v_cvt_pk_bf16_f32 v42, v44, v45
	v_cvt_pk_bf16_f32 v44, v48, v49
	v_cvt_pk_bf16_f32 v45, v46, v47
	v_cvt_pk_bf16_f32 v43, v58, v59
	v_pk_fma_f32 v[36:37], v[114:115], v[52:53], v[36:37] op_sel_hi:[0,1,1] neg_lo:[0,0,1] neg_hi:[0,0,1]
	v_pk_fma_f32 v[40:41], v[114:115], v[56:57], v[40:41] op_sel_hi:[0,1,1] neg_lo:[0,0,1] neg_hi:[0,0,1]
	v_pk_fma_f32 v[38:39], v[114:115], v[54:55], v[38:39] op_sel_hi:[0,1,1] neg_lo:[0,0,1] neg_hi:[0,0,1]
	v_and_b32_e32 v59, 64, v226
	v_xor_b32_e32 v58, 32, v226
	v_add_u32_e32 v59, 64, v59
	v_cmp_lt_i32_e32 vcc, v58, v59
	v_lshlrev_b32_e32 v178, 1, v32
	v_lshl_add_u64 v[32:33], s[60:61], 0, v[178:179]
	v_lshlrev_b32_e32 v178, 1, v72
	s_mov_b64 s[46:47], 0
	s_waitcnt vmcnt(0)
; __device__ __forceinline__ unsigned pk2(float lo, float hi) { f32v2 v = {lo, hi}; bf16v2 r = __builtin_convertvector(v, bf16v2); return __builtin_bit_cast(unsigned, r); }
; __device__ __forceinline__ void attn_unit(const bf16* Q, const bf16* Kb, const bf16* VT, bf16* OSB, int wu, int lane) {
;     const int h = wu & 7, blk = wu >> 3, qblk = blk & 255, b = blk >> 8;
;     const int r = lane & 31, hh = lane >> 5;
;     const int pr = (r & 19) | ((r & 8) >> 1) | ((r & 4) << 1);
;     const size_t tok0 = (size_t)b * SEQ + (size_t)qblk * 32;
;     bf16x8 qf[4];
;     { const bf16* qp = Q + (tok0 + r) * 512 + h * 64 + 8 * hh;
; #pragma unroll
;       for (int kk = 0; kk < 4; ++kk) qf[kk] = *(const bf16x8*)(qp + kk * 16); }
;     const bf16* kbase = Kb + ((size_t)b * SEQ + pr) * 512 + h * 64 + 8 * hh;
;     const bf16* vbase = VT + ((size_t)b * (SEQ / 32) * 512 + h * 64 + r) * 32 + 8 * hh;
;     bf16x8 kf[4], vf[2][2];
;     { const bf16* kp = kbase + (size_t)qblk * 32 * 512; const bf16* vp = vbase + (size_t)qblk * (512 * 32);
; #pragma unroll
;       for (int kk = 0; kk < 4; ++kk) kf[kk] = *(const bf16x8*)(kp + kk * 16);
; #pragma unroll
;       for (int mt = 0; mt < 2; ++mt)
; #pragma unroll
;           for (int s = 0; s < 2; ++s) vf[mt][s] = *(const bf16x8*)(vp + mt * 32 * 32 + 16 * s); }
; __device__ __forceinline__ void pool_unit(const float* P, const bf16* WPT, bf16* OPOOL, int pu, int lane) {
;     ...
;     bf16* op = OPOOL + (size_t)tok * 256 + g * 64;
; #pragma unroll
;     for (int gp = 0; gp < 2; ++gp) {
;         const int g0 = 2 * gp, g1 = 2 * gp + 1;
;         v2u a, b;
;         a.x = pk2(acc0[4 * g0], acc0[4 * g0 + 1]); a.y = pk2(acc0[4 * g0 + 2], acc0[4 * g0 + 3]); b.x = pk2(acc0[4 * g1], acc0[4 * g1 + 1]); b.y = pk2(acc0[4 * g1 + 2], acc0[4 * g1 + 3]);
;         *(v4u*)(op + 8 * (hh ? g1 : g0)) = pair_widen(a, b, hh);
;         a.x = pk2(acc1[4 * g0], acc1[4 * g0 + 1]); a.y = pk2(acc1[4 * g0 + 2], acc1[4 * g0 + 3]); b.x = pk2(acc1[4 * g1], acc1[4 * g1 + 1]); b.y = pk2(acc1[4 * g1 + 2], acc1[4 * g1 + 3]);
;         *(v4u*)(op + 32 + 8 * (hh ? g1 : g0)) = pair_widen(a, b, hh);
;     }
	v_mfma_f32_32x32x16_bf16 v[0:15], v[24:27], v[20:23], 0
	s_waitcnt vmcnt(2)
	v_mfma_f32_32x32x16_bf16 v[0:15], v[102:105], v[66:69], v[0:15]
	global_load_dwordx4 v[96:99], v[90:91], off
	global_load_dwordx4 v[100:103], v[82:83], off offset:96
	global_load_dwordx4 v[46:49], v[92:93], off
	v_mfma_f32_32x32x16_bf16 v[16:31], v[28:31], v[20:23], 0
	s_waitcnt vmcnt(4)
	v_mfma_f32_32x32x16_bf16 v[16:31], v[106:109], v[66:69], v[16:31]
	s_waitcnt vmcnt(3)
	v_mfma_f32_32x32x16_bf16 v[0:15], v[110:113], v[42:45], v[0:15]
	s_waitcnt vmcnt(0)
	v_mfma_f32_32x32x16_bf16 v[16:31], v[96:99], v[42:45], v[16:31]
	v_fma_f32 v42, v114, v50, -v34
	v_fma_f32 v43, v114, v51, -v35
	v_cvt_pk_bf16_f32 v34, v36, v37
	v_cvt_pk_bf16_f32 v35, v42, v43
	v_cvt_pk_bf16_f32 v36, v40, v41
	v_cvt_pk_bf16_f32 v37, v38, v39
	v_cndmask_b32_e32 v42, v226, v58, vcc
	v_lshlrev_b32_e32 v42, 2, v42
	s_waitcnt vmcnt(1)
	v_mfma_f32_32x32x16_bf16 v[0:15], v[100:103], v[34:37], v[0:15]
	v_lshl_add_u64 v[38:39], v[32:33], 0, v[178:179]
	v_lshlrev_b32_e32 v178, 1, v74
	v_lshl_add_u64 v[40:41], v[32:33], 0, v[178:179]
	s_waitcnt vmcnt(0)
	v_mfma_f32_32x32x16_bf16 v[16:31], v[46:49], v[34:37], v[16:31]
	s_nop 6
	v_cvt_pk_bf16_f32 v0, v0, v1
	v_cvt_pk_bf16_f32 v1, v2, v3
	v_cvt_pk_bf16_f32 v2, v4, v5
	v_cvt_pk_bf16_f32 v3, v6, v7
	v_cvt_pk_bf16_f32 v12, v12, v13
	v_cvt_pk_bf16_f32 v13, v14, v15
	v_cndmask_b32_e64 v4, v2, v0, s[4:5]
	v_cvt_pk_bf16_f32 v16, v16, v17
	v_cvt_pk_bf16_f32 v17, v18, v19
	v_cvt_pk_bf16_f32 v19, v22, v23
	v_cvt_pk_bf16_f32 v22, v24, v25
	v_cvt_pk_bf16_f32 v23, v26, v27
	v_cvt_pk_bf16_f32 v24, v28, v29
	v_cvt_pk_bf16_f32 v25, v30, v31
	v_cvt_pk_bf16_f32 v18, v20, v21
	v_cvt_pk_bf16_f32 v20, v8, v9
	v_cvt_pk_bf16_f32 v21, v10, v11
	v_cndmask_b32_e64 v5, v3, v1, s[4:5]
	v_cndmask_b32_e64 v10, v24, v22, s[4:5]
	v_cndmask_b32_e64 v11, v25, v23, s[4:5]
	v_cndmask_b32_e64 v6, v18, v16, s[4:5]
	v_cndmask_b32_e64 v7, v19, v17, s[4:5]
	v_cndmask_b32_e64 v8, v12, v20, s[4:5]
	v_cndmask_b32_e64 v9, v13, v21, s[4:5]
	ds_bpermute_b32 v4, v42, v4
	ds_bpermute_b32 v5, v42, v5
	ds_bpermute_b32 v28, v42, v10
	ds_bpermute_b32 v29, v42, v11
	ds_bpermute_b32 v14, v42, v6
	ds_bpermute_b32 v15, v42, v7
	ds_bpermute_b32 v26, v42, v8
	ds_bpermute_b32 v27, v42, v9
	s_waitcnt lgkmcnt(0)
	v_cndmask_b32_e64 v7, v5, v3, s[4:5]
	v_cndmask_b32_e64 v6, v4, v2, s[4:5]
	v_cndmask_b32_e64 v5, v1, v5, s[4:5]
	v_cndmask_b32_e64 v4, v0, v4, s[4:5]
	s_waitcnt lgkmcnt(4)
	v_cndmask_b32_e64 v3, v29, v25, s[4:5]
	v_cndmask_b32_e64 v2, v28, v24, s[4:5]
	v_cndmask_b32_e64 v1, v23, v29, s[4:5]
	v_cndmask_b32_e64 v0, v22, v28, s[4:5]
	s_waitcnt lgkmcnt(2)
	v_cndmask_b32_e64 v11, v15, v19, s[4:5]
	v_cndmask_b32_e64 v10, v14, v18, s[4:5]
	v_cndmask_b32_e64 v9, v17, v15, s[4:5]
	v_cndmask_b32_e64 v8, v16, v14, s[4:5]
	s_waitcnt lgkmcnt(0)
	v_cndmask_b32_e64 v15, v27, v13, s[4:5]
	v_cndmask_b32_e64 v14, v26, v12, s[4:5]
	v_cndmask_b32_e64 v13, v21, v27, s[4:5]
	v_cndmask_b32_e64 v12, v20, v26, s[4:5]
	global_store_dwordx4 v[38:39], v[4:7], off
	global_store_dwordx4 v[38:39], v[8:11], off offset:64
	global_store_dwordx4 v[40:41], v[12:15], off
.LBB0_115:
	s_and_b64 vcc, exec, s[46:47]
	s_cbranch_vccz .LBB0_110
	s_ashr_i32 s56, s96, 11
	s_bfe_u32 s42, s96, 0x80003
	s_ashr_i32 s57, s56, 31
	s_lshl_b64 s[64:65], s[56:57], 13
	s_lshl_b32 s41, s42, 5
	s_or_b32 s41, s64, s41
	v_or_b32_e32 v96, s41, v86
	s_lshl_b32 s41, s96, 6
	v_mov_b32_e32 v1, s65
	v_or_b32_e32 v0, s64, v76
	v_readlane_b32 s58, v253, 8
	s_and_b32 s41, s41, 0x1c0
	v_lshlrev_b64 v[0:1], 10, v[0:1]
	v_readlane_b32 s59, v253, 9
	s_lshl_b32 s46, s41, 1
	s_mov_b32 s47, s95
	v_lshl_add_u64 v[0:1], s[58:59], 0, v[0:1]
	v_mov_b32_e32 v95, v179
	v_lshl_add_u64 v[0:1], v[0:1], 0, s[46:47]
	v_lshl_add_u64 v[98:99], v[0:1], 0, v[94:95]
	s_lshl_b32 s94, s42, 15
	v_lshl_add_u64 v[6:7], v[98:99], 0, s[94:95]
	global_load_dwordx4 v[0:3], v[6:7], off
	v_mov_b32_e32 v97, s65
	v_lshlrev_b64 v[4:5], 10, v[96:97]
	v_lshl_add_u64 v[4:5], s[92:93], 0, v[4:5]
	v_lshl_add_u64 v[4:5], v[4:5], 0, s[46:47]
	v_lshl_add_u64 v[28:29], v[4:5], 0, v[94:95]
	global_load_dwordx4 v[48:51], v[28:29], off
	global_load_dwordx4 v[16:19], v[6:7], off offset:32
	global_load_dwordx4 v[52:55], v[28:29], off offset:32
	global_load_dwordx4 v[20:23], v[6:7], off offset:64
	global_load_dwordx4 v[56:59], v[28:29], off offset:64
	global_load_dwordx4 v[24:27], v[6:7], off offset:96
	global_load_dwordx4 v[60:63], v[28:29], off offset:96
	v_xor_b32_e32 v28, 32, v226
	s_lshl_b64 s[56:57], s[56:57], 17
	s_or_b32 s41, s56, s41
	s_waitcnt vmcnt(0)
	v_mfma_f32_32x32x16_bf16 v[0:15], v[0:3], v[48:51], 0
	s_waitcnt vmcnt(4)
	v_mfma_f32_32x32x16_bf16 v[0:15], v[16:19], v[52:55], v[0:15]
	v_and_b32_e32 v16, 64, v226
	v_add_u32_e32 v16, 64, v16
	v_cmp_lt_i32_e32 vcc, v28, v16
	v_mov_b32_e32 v17, s57
	s_nop 0
	v_cndmask_b32_e32 v16, v226, v28, vcc
	v_lshlrev_b32_e32 v73, 2, v16
	s_waitcnt vmcnt(2)
	v_mfma_f32_32x32x16_bf16 v[0:15], v[20:23], v[56:59], v[0:15]
	v_or_b32_e32 v16, s41, v86
	v_lshlrev_b64 v[16:17], 6, v[16:17]
	v_lshl_add_u64 v[100:101], v[78:79], 0, v[16:17]
	v_lshl_add_u64 v[36:37], v[100:101], 0, s[94:95]
	global_load_dwordx4 v[16:19], v[36:37], off
	global_load_dwordx4 v[32:35], v[36:37], off offset:32
	s_waitcnt vmcnt(2)
; #define MFMA32(a, b, c) __builtin_amdgcn_mfma_f32_32x32x16_bf16((a), (b), (c), 0, 0, 0)
; __device__ __forceinline__ void attn_unit(const bf16* Q, const bf16* Kb, const bf16* VT, bf16* OSB, int wu, int lane) {
;     ...
;         for (int kk = 0; kk < 4; ++kk) sc = MFMA32(kf[kk], qf[kk], sc);
;         const int lim = (kt == qblk) ? r : 64;
;         float ln[16], ls[16];
; #pragma unroll
;         for (int i = 0; i < 16; ++i) {
;             const float z = sc[i];
;             const float l2 = __builtin_amdgcn_logf(1.0f + __builtin_amdgcn_exp2f(-fabsf(z)));
;             const float sp = fmaxf(z, 0.f) + l2;
;             const bool valid = (16 * (i >> 3) + 8 * hh + (i & 7)) < lim;
;             ln[i] = valid ? -sp : 0.f;
;             ls[i] = valid ? z - sp : -1e30f;
;         }
;         float ex[16], gs[2];
; #pragma unroll
;         for (int s = 0; s < 2; ++s) { float run = 0.f;
; #pragma unroll
;             for (int j = 7; j >= 0; --j) { ex[8 * s + j] = run; run += ln[8 * s + j]; }
;             gs[s] = run; }
;         const float pg0 = __shfl_xor(gs[0], 32), pg1 = __shfl_xor(gs[1], 32);
	v_mfma_f32_32x32x16_bf16 v[0:15], v[24:27], v[60:63], v[0:15]
	s_nop 11
	v_exp_f32_e64 v20, -|v0|
	v_exp_f32_e64 v22, -|v1|
	v_exp_f32_e64 v24, -|v2|
	v_exp_f32_e64 v26, -|v3|
	v_exp_f32_e64 v28, -|v4|
	v_exp_f32_e64 v30, -|v5|
	v_exp_f32_e64 v38, -|v6|
	v_exp_f32_e64 v42, -|v8|
	v_add_f32_e32 v20, 1.0, v20
	v_add_f32_e32 v22, 1.0, v22
	v_add_f32_e32 v24, 1.0, v24
	v_add_f32_e32 v26, 1.0, v26
	v_add_f32_e32 v28, 1.0, v28
	v_add_f32_e32 v30, 1.0, v30
	v_add_f32_e32 v38, 1.0, v38
	v_add_f32_e32 v42, 1.0, v42
	v_log_f32_e32 v20, v20
	v_log_f32_e32 v22, v22
	v_log_f32_e32 v24, v24
	v_log_f32_e32 v26, v26
	v_log_f32_e32 v28, v28
	v_log_f32_e32 v30, v30
	v_log_f32_e32 v38, v38
	v_log_f32_e32 v42, v42
	v_max_f32_e32 v21, v0, v0
	v_exp_f32_e64 v44, -|v9|
	v_max_f32_e32 v23, v1, v1
	v_max_f32_e32 v25, v2, v2
	v_max_f32_e32 v27, v3, v3
	v_max_f32_e32 v29, v4, v4
	v_max_f32_e32 v31, v5, v5
	v_max_f32_e32 v39, v6, v6
	v_max_f32_e32 v43, v8, v8
	v_max_f32_e32 v21, 0, v21
	v_max_f32_e32 v23, 0, v23
	v_max_f32_e32 v25, 0, v25
	v_max_f32_e32 v27, 0, v27
	v_max_f32_e32 v29, 0, v29
	v_max_f32_e32 v31, 0, v31
	v_max_f32_e32 v39, 0, v39
	v_max_f32_e32 v43, 0, v43
	v_add_f32_e32 v20, v21, v20
	v_add_f32_e32 v21, v23, v22
	v_add_f32_e32 v22, v25, v24
	v_add_f32_e32 v23, v27, v26
	v_add_f32_e32 v24, v29, v28
	v_add_f32_e32 v25, v31, v30
	v_add_f32_e32 v26, v39, v38
	v_add_f32_e32 v28, v43, v42
	v_sub_f32_e32 v0, v0, v20
	v_add_f32_e32 v44, 1.0, v44
	v_cndmask_b32_e64 v30, 0, -v20, s[6:7]
	v_cndmask_b32_e64 v20, 0, -v21, s[8:9]
	v_sub_f32_e32 v1, v1, v21
	v_cndmask_b32_e64 v21, 0, -v22, s[10:11]
	v_sub_f32_e32 v2, v2, v22
	v_cndmask_b32_e64 v22, 0, -v23, s[12:13]
	v_sub_f32_e32 v3, v3, v23
	v_cndmask_b32_e64 v23, 0, -v24, s[14:15]
	v_sub_f32_e32 v4, v4, v24
	v_cndmask_b32_e64 v24, 0, -v25, s[16:17]
	v_sub_f32_e32 v5, v5, v25
	v_cndmask_b32_e64 v25, 0, -v26, s[18:19]
	v_sub_f32_e32 v6, v6, v26
	v_cndmask_b32_e64 v26, 0, -v28, s[22:23]
	v_sub_f32_e32 v8, v8, v28
	v_cndmask_b32_e64 v28, v228, v0, s[6:7]
	v_exp_f32_e64 v0, -|v10|
	v_log_f32_e32 v44, v44
	v_max_f32_e32 v45, v9, v9
	v_max_f32_e32 v45, 0, v45
	v_add_f32_e32 v0, 1.0, v0
	v_add_f32_e32 v29, v45, v44
	v_log_f32_e32 v0, v0
	v_cndmask_b32_e64 v31, v228, v1, s[8:9]
	v_cndmask_b32_e64 v178, v228, v6, s[18:19]
	v_cndmask_b32_e64 v6, v228, v8, s[22:23]
	v_cndmask_b32_e64 v1, 0, -v29, s[24:25]
	v_sub_f32_e32 v8, v9, v29
	v_exp_f32_e64 v29, -|v11|
	v_max_f32_e32 v9, v10, v10
	v_max_f32_e32 v9, 0, v9
	v_add_f32_e32 v0, v9, v0
	v_cndmask_b32_e64 v9, 0, -v0, s[26:27]
	v_sub_f32_e32 v0, v10, v0
	v_add_f32_e32 v10, 1.0, v29
	v_log_f32_e32 v10, v10
	v_cndmask_b32_e64 v29, v228, v0, s[26:27]
	v_max_f32_e32 v0, v11, v11
	v_max_f32_e32 v0, 0, v0
	v_add_f32_e32 v0, v0, v10
	v_exp_f32_e64 v10, -|v12|
	v_cndmask_b32_e64 v38, 0, -v0, s[28:29]
	v_sub_f32_e32 v0, v11, v0
	v_cndmask_b32_e64 v11, v228, v0, s[28:29]
	v_add_f32_e32 v0, 1.0, v10
	v_log_f32_e32 v0, v0
	v_exp_f32_e64 v39, -|v13|
	v_max_f32_e32 v10, v12, v12
	v_max_f32_e32 v10, 0, v10
	v_exp_f32_e64 v40, -|v7|
	v_add_f32_e32 v0, v10, v0
	v_cndmask_b32_e64 v10, 0, -v0, s[30:31]
	v_sub_f32_e32 v0, v12, v0
	v_add_f32_e32 v12, 1.0, v39
	v_log_f32_e32 v12, v12
	v_add_f32_e32 v40, 1.0, v40
	v_cndmask_b32_e64 v39, v228, v0, s[30:31]
	v_max_f32_e32 v0, v13, v13
	v_log_f32_e32 v40, v40
	v_max_f32_e32 v0, 0, v0
	v_add_f32_e32 v0, v0, v12
	v_exp_f32_e64 v12, -|v14|
	v_max_f32_e32 v41, v7, v7
	v_max_f32_e32 v41, 0, v41
	v_add_f32_e32 v27, v41, v40
	v_cndmask_b32_e64 v40, 0, -v0, s[34:35]
	v_sub_f32_e32 v0, v13, v0
	v_cndmask_b32_e64 v13, v228, v0, s[34:35]
	v_add_f32_e32 v0, 1.0, v12
	v_log_f32_e32 v0, v0
	v_exp_f32_e64 v41, -|v15|
	v_max_f32_e32 v12, v14, v14
	v_max_f32_e32 v12, 0, v12
	v_add_f32_e32 v0, v12, v0
	v_cndmask_b32_e64 v12, 0, -v0, s[36:37]
	v_sub_f32_e32 v0, v14, v0
	v_add_f32_e32 v14, 1.0, v41
	v_log_f32_e32 v14, v14
	v_cndmask_b32_e64 v41, v228, v0, s[36:37]
	v_max_f32_e32 v0, v15, v15
	v_max_f32_e32 v0, 0, v0
	v_add_f32_e32 v14, v0, v14
	v_sub_f32_e32 v7, v7, v27
	v_sub_f32_e32 v0, 0, v27
	v_sub_f32_e32 v27, 0, v14
	v_cndmask_b32_e64 v27, 0, v27, s[38:39]
	v_cndmask_b32_e64 v0, 0, v0, s[20:21]
	v_add_f32_e32 v12, v12, v27
	v_add_f32_e32 v25, v25, v0
	v_add_f32_e32 v40, v40, v12
	v_add_f32_e32 v24, v24, v25
	v_add_f32_e32 v10, v10, v40
	v_add_f32_e32 v23, v23, v24
	v_add_f32_e32 v38, v38, v10
	v_add_f32_e32 v22, v22, v23
	v_add_f32_e32 v9, v9, v38
	v_add_f32_e32 v21, v21, v22
	v_add_f32_e32 v46, v1, v9
	v_add_f32_e32 v43, v26, v46
	v_add_f32_e32 v20, v20, v21
	ds_bpermute_b32 v42, v73, v43
	v_add_f32_e32 v45, v30, v20
	ds_bpermute_b32 v44, v73, v45
	v_sub_f32_e32 v14, v15, v14
	v_cndmask_b32_e64 v2, v228, v2, s[10:11]
	s_waitcnt lgkmcnt(0)
; #define MFMA32(a, b, c) __builtin_amdgcn_mfma_f32_32x32x16_bf16((a), (b), (c), 0, 0, 0)
; __device__ __forceinline__ void attn_unit(const bf16* Q, const bf16* Kb, const bf16* VT, bf16* OSB, int wu, int lane) {
;     ...
;         const float off1 = (hh == 0 ? pg1 : 0.f) + carry;
;         const float off0 = gs[1] + pg1 + (hh == 0 ? pg0 : 0.f) + carry;
;         float a0[8], a1[8];
; #pragma unroll
;         for (int j = 0; j < 8; ++j) { a0[j] = __builtin_amdgcn_exp2f(ls[j] + ex[j] + off0); a1[j] = __builtin_amdgcn_exp2f(ls[8 + j] + ex[8 + j] + off1); }
;         const bf16x8 p0 = pack8(a0), p1 = pack8(a1);
;         o0 = MFMA32(vf[0][0], p0, o0); o0 = MFMA32(vf[0][1], p1, o0);
;         o1 = MFMA32(vf[1][0], p0, o1); o1 = MFMA32(vf[1][1], p1, o1);
;         carry += (gs[0] + gs[1]) + (pg0 + pg1);
;         if (__all(carry < -60.f)) break;
	v_add_f32_e32 v1, 0, v42
	v_cndmask_b32_e64 v15, v1, 0, s[4:5]
	v_add_f32_e32 v1, v43, v42
	s_waitcnt lgkmcnt(0)
	v_cndmask_b32_e64 v26, v44, 0, s[4:5]
	v_cndmask_b32_e64 v3, v228, v3, s[12:13]
	v_cndmask_b32_e64 v4, v228, v4, s[14:15]
	v_cndmask_b32_e64 v5, v228, v5, s[16:17]
	v_add_f32_e32 v1, v26, v1
	v_add_f32_e32 v2, v2, v22
	v_add_f32_e32 v3, v3, v23
	v_add_f32_e32 v4, v4, v24
	v_add_f32_e32 v5, v5, v25
	v_pk_add_f32 v[0:1], v[0:1], v[178:179]
	v_add_f32_e32 v20, v28, v20
	v_add_f32_e32 v21, v31, v21
	v_add_f32_e32 v2, v2, v1
	v_add_f32_e32 v3, v3, v1
	v_add_f32_e32 v4, v4, v1
	v_add_f32_e32 v5, v5, v1
	v_add_f32_e32 v0, v0, v1
	v_add_f32_e32 v12, v13, v12
	v_add_f32_e32 v13, v20, v1
	v_add_f32_e32 v20, v21, v1
	v_exp_f32_e32 v2, v2
	v_exp_f32_e32 v3, v3
	v_exp_f32_e32 v4, v4
	v_exp_f32_e32 v5, v5
	v_exp_f32_e32 v21, v0
	v_add_f32_e32 v0, v27, v41
	v_add_f32_e32 v0, v15, v0
	v_exp_f32_e32 v41, v0
	v_add_f32_e32 v0, 0, v7
	v_cndmask_b32_e64 v8, v228, v8, s[24:25]
	v_cndmask_b32_e64 v0, v228, v0, s[20:21]
	v_add_f32_e32 v14, 0, v14
	v_add_f32_e32 v6, v6, v46
	v_add_f32_e32 v8, v8, v9
	v_add_f32_e32 v0, v0, v1
	v_cvt_pk_bf16_f32 v1, v2, v3
	v_cvt_pk_bf16_f32 v2, v4, v5
	v_cndmask_b32_e64 v4, v228, v14, s[38:39]
	v_add_f32_e32 v6, v15, v6
	v_add_f32_e32 v8, v15, v8
	v_exp_f32_e32 v13, v13
	v_exp_f32_e32 v20, v20
	v_exp_f32_e32 v7, v0
	v_add_f32_e32 v4, v15, v4
	v_exp_f32_e32 v6, v6
	v_exp_f32_e32 v8, v8
	v_exp_f32_e32 v4, v4
	v_cvt_pk_bf16_f32 v0, v13, v20
	v_cvt_pk_bf16_f32 v3, v21, v7
	v_add_f32_e32 v9, v29, v38
	v_cvt_pk_bf16_f32 v38, v6, v8
	s_waitcnt vmcnt(1)
	v_mfma_f32_32x32x16_bf16 v[16:31], v[16:19], v[0:3], 0
	v_cvt_pk_bf16_f32 v41, v41, v4
	global_load_dwordx4 v[4:7], v[36:37], off offset:2048
	v_add_f32_e32 v10, v11, v10
	v_add_f32_e32 v11, v39, v40
	v_add_f32_e32 v9, v15, v9
	v_add_f32_e32 v10, v15, v10
	v_add_f32_e32 v11, v15, v11
	v_add_f32_e32 v12, v15, v12
	v_exp_f32_e32 v9, v9
	v_exp_f32_e32 v10, v10
	v_exp_f32_e32 v11, v11
	v_exp_f32_e32 v12, v12
	v_cvt_pk_bf16_f32 v39, v9, v10
	v_cvt_pk_bf16_f32 v40, v11, v12
	s_waitcnt vmcnt(1)
	s_nop 0
	v_mfma_f32_32x32x16_bf16 v[16:31], v[32:35], v[38:41], v[16:31]
	global_load_dwordx4 v[32:35], v[36:37], off offset:2080
	s_waitcnt vmcnt(1)
	v_mfma_f32_32x32x16_bf16 v[0:15], v[4:7], v[0:3], 0
	s_waitcnt vmcnt(0)
	v_mfma_f32_32x32x16_bf16 v[0:15], v[32:35], v[38:41], v[0:15]
	v_add_f32_e64 v32, v44, v42
	v_add_f32_e64 v33, v45, v43
	v_add_f32_e32 v32, v32, v33
	v_cmp_gt_f32_e32 vcc, s53, v32
	s_cmp_eq_u64 vcc, exec
	s_cselect_b64 s[56:57], -1, 0
	s_cmp_eq_u32 s42, 0
	s_cselect_b64 s[64:65], -1, 0
	s_or_b64 s[56:57], s[64:65], s[56:57]
	s_and_b64 vcc, exec, s[56:57]
	s_cbranch_vccnz .LBB0_109
	s_addk_i32 s94, 0x8000
	s_add_i32 s41, s42, 1
	s_add_i32 s42, s42, -1
	v_add_f32_e32 v103, 0, v32
	s_mov_b64 s[64:65], s[94:95]
	s_branch .LBB0_119

; #define MFMA32(a, b, c) __builtin_amdgcn_mfma_f32_32x32x16_bf16((a), (b), (c), 0, 0, 0)
; __device__ __forceinline__ void attn_unit(const bf16* Q, const bf16* Kb, const bf16* VT, bf16* OSB, int wu, int lane) {
;     ...
;         bf16x8 kn[4], vn[2][2];
;         { const int ktn = kt > 0 ? kt - 1 : 0; const bf16* kp = kbase + (size_t)ktn * 32 * 512; const bf16* vp = vbase + (size_t)ktn * (512 * 32);
; #pragma unroll
;           for (int kk = 0; kk < 4; ++kk) kn[kk] = *(const bf16x8*)(kp + kk * 16);
; #pragma unroll
;           for (int mt = 0; mt < 2; ++mt)
; #pragma unroll
;               for (int s = 0; s < 2; ++s) vn[mt][s] = *(const bf16x8*)(vp + mt * 32 * 32 + 16 * s); }
;         f32x16 sc;
; #pragma unroll
;         for (int i = 0; i < 16; ++i) sc[i] = 0.f;
; #pragma unroll
;         for (int kk = 0; kk < 4; ++kk) sc = MFMA32(kf[kk], qf[kk], sc);
;         const int lim = (kt == qblk) ? r : 64;
;         float ln[16], ls[16];
; #pragma unroll
;         for (int i = 0; i < 16; ++i) {
;             const float z = sc[i];
;             const float l2 = __builtin_amdgcn_logf(1.0f + __builtin_amdgcn_exp2f(-fabsf(z)));
;             const float sp = fmaxf(z, 0.f) + l2;
;             const bool valid = (16 * (i >> 3) + 8 * hh + (i & 7)) < lim;
;             ln[i] = valid ? -sp : 0.f;
;             ls[i] = valid ? z - sp : -1e30f;
.LBB0_119:
	v_lshl_add_u64 v[104:105], v[98:99], 0, s[64:65]
	global_load_dwordx4 v[32:35], v[104:105], off
	global_load_dwordx4 v[64:67], v[104:105], off offset:32
	global_load_dwordx4 v[68:71], v[104:105], off offset:64
	global_load_dwordx4 v[106:109], v[104:105], off offset:96
	v_mov_b32_e32 v110, v179
	v_mov_b32_e32 v112, v179
	v_lshl_add_u64 v[104:105], v[100:101], 0, s[64:65]
	s_waitcnt vmcnt(3)
	v_mfma_f32_32x32x16_bf16 v[32:47], v[32:35], v[48:51], 0
	s_waitcnt vmcnt(2)
	v_mfma_f32_32x32x16_bf16 v[32:47], v[64:67], v[52:55], v[32:47]
	s_waitcnt vmcnt(1)
	v_mfma_f32_32x32x16_bf16 v[32:47], v[68:71], v[56:59], v[32:47]
	global_load_dwordx4 v[68:71], v[104:105], off
	global_load_dwordx4 v[64:67], v[104:105], off offset:32
	s_waitcnt vmcnt(2)
	v_mfma_f32_32x32x16_bf16 v[32:47], v[106:109], v[60:63], v[32:47]
	s_nop 11
	v_exp_f32_e64 v87, -|v33|
	v_exp_f32_e64 v132, -|v38|
	v_exp_f32_e64 v133, -|v39|
	v_exp_f32_e64 v137, -|v43|
	v_exp_f32_e64 v138, -|v44|
	v_exp_f32_e64 v139, -|v45|
	v_exp_f32_e64 v140, -|v46|
	v_exp_f32_e64 v141, -|v47|
	v_exp_f32_e64 v75, -|v32|
	v_exp_f32_e64 v109, -|v35|
	v_exp_f32_e64 v130, -|v36|
	v_exp_f32_e64 v131, -|v37|
	v_exp_f32_e64 v136, -|v42|
	v_exp_f32_e64 v102, -|v34|
	v_exp_f32_e64 v134, -|v40|
	v_exp_f32_e64 v135, -|v41|
	v_max_f32_e32 v95, v33, v33
	v_max_f32_e32 v120, v38, v38
	v_max_f32_e32 v122, v39, v39
	v_max_f32_e32 v123, v40, v40
	v_max_f32_e32 v124, v41, v41
	v_max_f32_e32 v125, v42, v42
	v_max_f32_e32 v126, v43, v43
	v_max_f32_e32 v127, v44, v44
	v_max_f32_e32 v128, v45, v45
	v_max_f32_e32 v142, v47, v47
	v_max_f32_e32 v77, v32, v32
	v_max_f32_e32 v117, v35, v35
	v_mov_b32_e32 v111, v38
	v_mov_b32_e32 v38, v35
	v_max_f32_e32 v115, 0, v95
	v_max_f32_e32 v121, 0, v120
	v_max_f32_e32 v120, 0, v122
	v_max_f32_e32 v122, 0, v123
	v_max_f32_e32 v123, 0, v124
	v_max_f32_e32 v124, 0, v125
	v_max_f32_e32 v125, 0, v126
	v_max_f32_e32 v126, 0, v127
	v_max_f32_e32 v127, 0, v128
	v_max_f32_e32 v128, 0, v142
	v_add_f32_e32 v35, 1.0, v87
	v_add_f32_e32 v87, 1.0, v132
	v_add_f32_e32 v95, 1.0, v133
	v_add_f32_e32 v142, 1.0, v137
	v_add_f32_e32 v143, 1.0, v138
	v_add_f32_e32 v144, 1.0, v139
	v_add_f32_e32 v145, 1.0, v140
	v_add_f32_e32 v146, 1.0, v141
	v_max_f32_e32 v107, v34, v34
	v_max_f32_e32 v129, v46, v46
	v_mov_b32_e32 v106, v33
	v_mov_b32_e32 v113, v46
	v_mov_b32_e32 v46, v43
	v_max_f32_e32 v114, 0, v77
	v_add_f32_e32 v33, 1.0, v75
	v_add_f32_e32 v43, 1.0, v109
	v_add_f32_e32 v75, 1.0, v130
	v_add_f32_e32 v77, 1.0, v131
	v_add_f32_e32 v109, 1.0, v136
	v_log_f32_e32 v137, v87
	v_log_f32_e32 v136, v95
	v_log_f32_e32 v141, v142
	v_log_f32_e32 v142, v143
	v_log_f32_e32 v143, v144
	v_log_f32_e32 v145, v145
	v_log_f32_e32 v144, v146
	v_mov_b32_e32 v108, v41
	v_max_f32_e32 v116, 0, v107
	v_add_f32_e32 v41, 1.0, v102
	v_add_f32_e32 v102, 1.0, v134
	v_add_f32_e32 v107, 1.0, v135
	v_log_f32_e32 v134, v75
	v_log_f32_e32 v135, v77
	v_log_f32_e32 v130, v33
	v_log_f32_e32 v131, v35
	v_max_f32_e32 v118, v36, v36
	v_max_f32_e32 v119, v37, v37
	v_max_f32_e32 v129, 0, v129
	v_max_f32_e32 v118, 0, v118
	v_max_f32_e32 v119, 0, v119
	v_pk_add_f32 v[120:121], v[120:121], v[136:137]
	v_pk_add_f32 v[128:129], v[128:129], v[144:145]
	v_log_f32_e32 v132, v41
	v_log_f32_e32 v133, v43
	v_log_f32_e32 v140, v109
	v_pk_add_f32 v[118:119], v[118:119], v[134:135]
	v_pk_add_f32 v[126:127], v[126:127], v[142:143]
	v_pk_add_f32 v[110:111], v[110:111], v[120:121] neg_lo:[0,1] neg_hi:[0,1]
	v_pk_add_f32 v[112:113], v[112:113], v[128:129] neg_lo:[0,1] neg_hi:[0,1]
	v_log_f32_e32 v138, v102
	v_log_f32_e32 v139, v107
	v_pk_add_f32 v[114:115], v[114:115], v[130:131]
	v_sub_f32_e32 v130, v39, v120
	v_mov_b32_e32 v120, v119
	v_sub_f32_e32 v137, v47, v128
	v_mov_b32_e32 v128, v127
	v_pk_mov_b32 v[142:143], v[36:37], v[110:111] op_sel:[1,0]
	v_pk_mov_b32 v[144:145], v[44:45], v[112:113] op_sel:[1,0]
	v_pk_add_f32 v[120:121], v[142:143], v[120:121] neg_lo:[0,1] neg_hi:[0,1]
	v_pk_add_f32 v[128:129], v[144:145], v[128:129] neg_lo:[0,1] neg_hi:[0,1]
	v_max_f32_e32 v117, 0, v117
	v_mov_b32_e32 v37, v121
	v_mov_b32_e32 v45, v129
	v_pk_add_f32 v[116:117], v[116:117], v[132:133]
	v_pk_add_f32 v[124:125], v[124:125], v[140:141]
	v_pk_add_f32 v[36:37], v[36:37], v[118:119] neg_lo:[0,1] neg_hi:[0,1]
	v_pk_add_f32 v[44:45], v[44:45], v[126:127] neg_lo:[0,1] neg_hi:[0,1]
	v_pk_add_f32 v[122:123], v[122:123], v[138:139]
	v_pk_mov_b32 v[132:133], v[116:117], v[118:119] op_sel:[1,0]
	v_pk_mov_b32 v[138:139], v[124:125], v[126:127] op_sel:[1,0]
	v_mov_b32_e32 v39, v37
	v_mov_b32_e32 v47, v45
	v_pk_add_f32 v[38:39], v[38:39], v[132:133] neg_lo:[0,1] neg_hi:[0,1]
	v_pk_add_f32 v[46:47], v[46:47], v[138:139] neg_lo:[0,1] neg_hi:[0,1]
	v_mov_b32_e32 v35, v39
	v_mov_b32_e32 v43, v47
	v_pk_add_f32 v[34:35], v[34:35], v[116:117] neg_lo:[0,1] neg_hi:[0,1]
	v_pk_add_f32 v[42:43], v[42:43], v[124:125] neg_lo:[0,1] neg_hi:[0,1]
	v_pk_mov_b32 v[134:135], v[114:115], v[116:117] op_sel:[1,0]
	v_pk_mov_b32 v[140:141], v[122:123], v[124:125] op_sel:[1,0]
	v_mov_b32_e32 v107, v35
	v_mov_b32_e32 v109, v43
	v_pk_add_f32 v[106:107], v[106:107], v[134:135] neg_lo:[0,1] neg_hi:[0,1]
	v_pk_add_f32 v[108:109], v[108:109], v[140:141] neg_lo:[0,1] neg_hi:[0,1]
	v_mov_b32_e32 v33, v107
	v_mov_b32_e32 v41, v109
	v_pk_add_f32 v[32:33], v[32:33], v[114:115] neg_lo:[0,1] neg_hi:[0,1]
	v_pk_add_f32 v[40:41], v[40:41], v[122:123] neg_lo:[0,1] neg_hi:[0,1]
	v_pk_add_f32 v[114:115], v[32:33], v[114:115] op_sel:[1,0] op_sel_hi:[0,1] neg_lo:[0,1] neg_hi:[0,1]
	v_pk_add_f32 v[116:117], v[40:41], v[122:123] op_sel:[1,0] op_sel_hi:[0,1] neg_lo:[0,1] neg_hi:[0,1]
	ds_bpermute_b32 v118, v73, v116
	ds_bpermute_b32 v122, v73, v114
	v_mov_b32_e32 v102, v179
	v_add_f32_e32 v32, v32, v33
	v_add_f32_e32 v33, v106, v107
	s_waitcnt lgkmcnt(1)
; #define MFMA32(a, b, c) __builtin_amdgcn_mfma_f32_32x32x16_bf16((a), (b), (c), 0, 0, 0)
; __device__ __forceinline__ void attn_unit(const bf16* Q, const bf16* Kb, const bf16* VT, bf16* OSB, int wu, int lane) {
;     ...
;         const float off1 = (hh == 0 ? pg1 : 0.f) + carry;
;         const float off0 = gs[1] + pg1 + (hh == 0 ? pg0 : 0.f) + carry;
;         float a0[8], a1[8];
; #pragma unroll
;         for (int j = 0; j < 8; ++j) { a0[j] = __builtin_amdgcn_exp2f(ls[j] + ex[j] + off0); a1[j] = __builtin_amdgcn_exp2f(ls[8 + j] + ex[8 + j] + off1); }
;         const bf16x8 p0 = pack8(a0), p1 = pack8(a1);
;         o0 = MFMA32(vf[0][0], p0, o0); o0 = MFMA32(vf[0][1], p1, o0);
;         o1 = MFMA32(vf[1][0], p0, o1); o1 = MFMA32(vf[1][1], p1, o1);
;         carry += (gs[0] + gs[1]) + (pg0 + pg1);
;         if (__all(carry < -60.f)) break;
; #pragma unroll
;         for (int kk = 0; kk < 4; ++kk) kf[kk] = kn[kk];
; #pragma unroll
;         for (int mt = 0; mt < 2; ++mt)
; #pragma unroll
;             for (int s = 0; s < 2; ++s) vf[mt][s] = vn[mt][s];
	v_add_f32_e32 v75, v116, v118
	s_waitcnt lgkmcnt(0)
	v_cndmask_b32_e64 v77, v122, 0, s[4:5]
	v_add_f32_e32 v131, v77, v75
	v_pk_add_f32 v[124:125], v[102:103], v[130:131]
	v_add_f32_e32 v34, v34, v35
	v_add_f32_e32 v35, v38, v39
	v_add_f32_e32 v36, v36, v37
	v_add_f32_e32 v37, v120, v121
	v_add_f32_e32 v38, v110, v111
	v_add_f32_e32 v32, v32, v125
	v_add_f32_e32 v33, v33, v125
	v_add_f32_e32 v34, v34, v125
	v_add_f32_e32 v35, v35, v125
	v_add_f32_e32 v36, v36, v125
	v_add_f32_e32 v37, v37, v125
	v_add_f32_e32 v38, v38, v125
	v_add_f32_e32 v39, v124, v125
	v_exp_f32_e32 v32, v32
	v_exp_f32_e32 v33, v33
	v_exp_f32_e32 v34, v34
	v_exp_f32_e32 v35, v35
	v_exp_f32_e32 v36, v36
	v_exp_f32_e32 v37, v37
	v_exp_f32_e32 v38, v38
	v_exp_f32_e32 v39, v39
	v_cvt_pk_bf16_f32 v32, v32, v33
	v_cvt_pk_bf16_f32 v33, v34, v35
	v_cvt_pk_bf16_f32 v34, v36, v37
	v_cvt_pk_bf16_f32 v35, v38, v39
	global_load_dwordx4 v[36:39], v[104:105], off offset:2048
	v_cndmask_b32_e64 v178, v118, 0, s[4:5]
	v_mov_b32_e32 v136, v103
	v_pk_add_f32 v[106:107], v[136:137], v[178:179]
	v_add_f32_e32 v40, v40, v41
	v_add_f32_e32 v41, v108, v109
	v_add_f32_e32 v42, v42, v43
	v_add_f32_e32 v43, v46, v47
	v_add_f32_e32 v44, v44, v45
	v_add_f32_e32 v45, v128, v129
	v_add_f32_e32 v46, v112, v113
	v_add_f32_e32 v40, v106, v40
	v_add_f32_e32 v41, v106, v41
	v_add_f32_e32 v42, v106, v42
	v_add_f32_e32 v43, v106, v43
	v_add_f32_e32 v44, v106, v44
	v_add_f32_e32 v45, v106, v45
	v_add_f32_e32 v46, v106, v46
	v_add_f32_e32 v47, v106, v107
	v_exp_f32_e32 v40, v40
	v_exp_f32_e32 v41, v41
	v_exp_f32_e32 v42, v42
	v_exp_f32_e32 v43, v43
	v_exp_f32_e32 v44, v44
	v_exp_f32_e32 v45, v45
	v_exp_f32_e32 v46, v46
	v_exp_f32_e32 v47, v47
	v_cvt_pk_bf16_f32 v40, v40, v41
	v_cvt_pk_bf16_f32 v41, v42, v43
	v_cvt_pk_bf16_f32 v42, v44, v45
	v_cvt_pk_bf16_f32 v43, v46, v47
	global_load_dwordx4 v[44:47], v[104:105], off offset:2080
	s_waitcnt vmcnt(3)
	v_mfma_f32_32x32x16_bf16 v[16:31], v[68:71], v[32:35], v[16:31]
	v_mov_b32_e32 v123, v114
	v_mov_b32_e32 v119, v116
	s_waitcnt vmcnt(1)
	v_mfma_f32_32x32x16_bf16 v[0:15], v[36:39], v[32:35], v[0:15]
	v_add_f32_e64 v32, v122, v118
	v_add_f32_e64 v33, v123, v119
	v_add_f32_e32 v32, v32, v33
	v_add_f32_e32 v103, v103, v32
	v_cmp_gt_f32_e32 vcc, s53, v103
	s_cmp_eq_u64 vcc, exec
	s_mov_b64 vcc, -1
	v_mfma_f32_32x32x16_bf16 v[16:31], v[64:67], v[40:43], v[16:31]
	s_waitcnt vmcnt(0)
	v_mfma_f32_32x32x16_bf16 v[0:15], v[44:47], v[40:43], v[0:15]
	s_cbranch_scc1 .LBB0_118
	s_min_u32 s43, s42, 1
	s_sub_i32 s43, s41, s43
	s_add_i32 s94, s43, -2
	s_lshl_b64 s[64:65], s[94:95], 15
	s_add_i32 s41, s41, -1
	s_add_i32 s42, s42, -1
	s_cmp_lt_u32 s41, 2
	s_cselect_b64 vcc, -1, 0
	s_branch .LBB0_118
